# FFN up epilogues: per-row rstd computed once per workgroup and phase (same token rows for all its tiles), cached in 8 registers; later tiles skip the ssq loads and shuffles
# speedup vs baseline: 1.0072x; 1.0072x over previous
; #define GSYNC() do { LAS unsigned char* l_ = (LAS unsigned char*)lds; asm volatile("" : "+s"(l_)); unsigned char* w_ = args.ws; asm volatile("" : "+s"(w_)); int t_ = threadIdx.x; asm volatile("" : "+v"(t_)); xcd_barrier((unsigned*)(w_ + WS_CTL), (volatile LAS unsigned*)(l_ + LDS_MISC), __builtin_amdgcn_readfirstlane(t_ >> 6), t_ & 63); } while (0)
; __global__ void __launch_bounds__(NTHREADS, 2) mega_fwd(Args args) {
;     ...
;         if (gridDim.y > 1) grid.sync(); else GSYNC();
;         {   PHASE_PTRS
;             pg8::Gemm g{XB, (const bf16*)(ws + WS_W1A), M, 2 * FFH, DM, DM, DM}; pg8::StaticOrder S; S.init(M, 2 * FFH, G_, bx_);
;             EpiSwiglu E{ACT, SSQ};
;             pg8::gemm_phase<EpiSwiglu, pg8::StaticOrder, true, true>(ldsp, g, S, E);
.LBB0_134:
	s_add_i32 s101, s101, 1
	s_mov_b32 s32, 0
	s_mov_b64 s[4:5], 0
	s_waitcnt lgkmcnt(0)
	s_barrier
	v_readlane_b32 vcc_lo, v255, 22
	v_readlane_b32 vcc_hi, v255, 23
	v_lshlrev_b32_e32 v245, 2, v215
	v_and_b32_e32 v246, 28, v245
	v_add_u32_e32 v245, 0xe208000, v245
	v_add_u32_e32 v246, 0xe208000, v246
	s_nop 3
	global_load_dword v247, v246, vcc
	global_load_dword v248, v245, vcc
	global_load_dword v249, v245, vcc offset:256
	global_load_dword v250, v245, vcc offset:512
	global_load_dword v251, v245, vcc offset:768
	s_waitcnt vmcnt(0)
	v_xor_b32_e32 v248, v248, v247
	v_xor_b32_e32 v249, v249, v247
	v_xor_b32_e32 v250, v250, v247
	v_xor_b32_e32 v251, v251, v247
	v_or3_b32 v248, v248, v249, v250
	v_or_b32_e32 v248, v248, v251
	v_cmp_ne_u32_e32 vcc, 0, v248
	s_nop 1
	s_cmp_eq_u64 vcc, 0
	s_cselect_b32 s100, 1, 0

; __device__ __forceinline__ void row_rstd4(const float* ssq, int row0, int fq, float (&rs)[4]) {
;     f32x4 v[4];
; #pragma unroll
;     for (int m = 0; m < 4; ++m) v[m] = *(const f32x4*)(ssq + (size_t)(row0 + m * 16) * 16 + fq * 4);
; #pragma unroll
;     for (int m = 0; m < 4; ++m) { float t = (v[m][0] + v[m][1]) + (v[m][2] + v[m][3]); t += __shfl_xor(t, 16); t += __shfl_xor(t, 32); rs[m] = __builtin_amdgcn_rsqf(t * (1.f / DM) + EPS); }
; }
;     __device__ __forceinline__ void operator()(const f32x4 (&acc)[2][2][4][2], const pg8::Unit& u, int wr, int wc, int fr, int fq) const {
;     ...
;         for (int ai = 0; ai < 2; ++ai) { float rsv[4]; row_rstd4(ssq, row0 + ai * 128, fq, rsv);
; #pragma unroll
;             for (int m = 0; m < 4; ++m) {
;                 const int row = row0 + ai * 128 + m * 16; const float rs = rsv[m], c = -rs * LOG2E, rs2 = rs * rs;
;                 f32x4 e0 = acc[ai][0][m][0] * c, e1 = acc[ai][0][m][1] * c;
.LBB0_159:
	s_cmp_lg_u32 s32, 0
	s_cbranch_scc1 .Lrc_a0
	v_lshl_add_u32 v254, s24, 8, v148
	v_mov_b32_e32 v172, v254
	v_ashrrev_i32_e32 v173, 31, v172
	v_lshlrev_b64 v[172:173], 6, v[172:173]
	v_lshl_add_u64 v[172:173], v[134:135], 0, v[172:173]
	global_load_dwordx4 v[172:175], v[172:173], off
	v_add_u32_e32 v176, 16, v254
	v_ashrrev_i32_e32 v177, 31, v176
	v_lshlrev_b64 v[176:177], 6, v[176:177]
	v_lshl_add_u64 v[176:177], v[134:135], 0, v[176:177]
	global_load_dwordx4 v[176:179], v[176:177], off
	v_add_u32_e32 v180, 32, v254
	v_ashrrev_i32_e32 v181, 31, v180
	v_lshlrev_b64 v[180:181], 6, v[180:181]
	v_lshl_add_u64 v[180:181], v[134:135], 0, v[180:181]
	global_load_dwordx4 v[180:183], v[180:181], off
	v_add_u32_e32 v184, 48, v254
	v_ashrrev_i32_e32 v185, 31, v184
	v_lshlrev_b64 v[184:185], 6, v[184:185]
	v_lshl_add_u64 v[184:185], v[134:135], 0, v[184:185]
	global_load_dwordx4 v[184:187], v[184:185], off
	v_add_u32_e32 v188, 0x80, v254
	v_ashrrev_i32_e32 v189, 31, v188
	v_lshlrev_b64 v[188:189], 6, v[188:189]
	v_lshl_add_u64 v[188:189], v[134:135], 0, v[188:189]
	global_load_dwordx4 v[188:191], v[188:189], off
	v_add_u32_e32 v218, 0x90, v254
	v_ashrrev_i32_e32 v219, 31, v218
	v_lshlrev_b64 v[218:219], 6, v[218:219]
	v_lshl_add_u64 v[218:219], v[134:135], 0, v[218:219]
	global_load_dwordx4 v[218:221], v[218:219], off
	v_add_u32_e32 v222, 0xa0, v254
	v_ashrrev_i32_e32 v223, 31, v222
	v_lshlrev_b64 v[222:223], 6, v[222:223]
	v_lshl_add_u64 v[222:223], v[134:135], 0, v[222:223]
	global_load_dwordx4 v[222:225], v[222:223], off
	v_add_u32_e32 v226, 0xb0, v254
	v_ashrrev_i32_e32 v227, 31, v226
	v_lshlrev_b64 v[226:227], 6, v[226:227]
	v_lshl_add_u64 v[226:227], v[134:135], 0, v[226:227]
	global_load_dwordx4 v[226:229], v[226:227], off
	v_xor_b32_e32 v202, 16, v215
	v_xor_b32_e32 v214, 32, v215
	v_lshlrev_b32_e32 v202, 2, v202
	v_lshlrev_b32_e32 v214, 2, v214
.Lrc_a0:
	v_lshl_add_u32 v140, s24, 8, v148
	v_or_b32_e32 v146, 16, v140
	v_or_b32_e32 v144, 32, v140
	v_or_b32_e32 v142, 48, v140
	v_ashrrev_i32_e32 v143, 31, v142
	v_lshlrev_b64 v[164:165], 6, v[142:143]
	v_lshl_add_u64 v[164:165], v[134:135], 0, v[164:165]
	v_and_b32_e32 v143, 64, v215
	v_xor_b32_e32 v141, 16, v215
	v_add_u32_e32 v143, 64, v143
	v_xor_b32_e32 v145, 32, v215
	v_cmp_lt_i32_e32 vcc, v141, v143
	v_pk_mul_f32 v[126:127], v[118:119], v[126:127]
	v_pk_mul_f32 v[124:125], v[116:117], v[124:125]
	v_cndmask_b32_e32 v141, v215, v141, vcc
	v_cmp_lt_i32_e32 vcc, v145, v143
	v_lshlrev_b32_e32 v141, 2, v141
	v_pk_mul_f32 v[120:121], v[112:113], v[120:121]
	v_cndmask_b32_e32 v143, v215, v145, vcc
	v_lshlrev_b32_e32 v143, 2, v143
	v_pk_mul_f32 v[122:123], v[114:115], v[122:123]
	v_lshl_or_b32 v168, s70, 7, v150
	v_ashrrev_i32_e32 v169, 31, v168
	v_pk_mul_f32 v[100:101], v[108:109], v[100:101]
	v_pk_mul_f32 v[102:103], v[110:111], v[102:103]
	v_pk_mul_f32 v[98:99], v[106:107], v[98:99]
	v_pk_mul_f32 v[96:97], v[104:105], v[96:97]
	v_pk_mul_f32 v[84:85], v[92:93], v[84:85]
	v_pk_mul_f32 v[86:87], v[94:95], v[86:87]
	v_pk_mul_f32 v[82:83], v[90:91], v[82:83]
	v_pk_mul_f32 v[80:81], v[88:89], v[80:81]
	v_pk_mul_f32 v[68:69], v[76:77], v[68:69]
	v_pk_mul_f32 v[70:71], v[78:79], v[70:71]
	v_pk_mul_f32 v[66:67], v[74:75], v[66:67]
	v_pk_mul_f32 v[64:65], v[72:73], v[64:65]
	v_pk_mul_f32 v[52:53], v[60:61], v[52:53]
	v_pk_mul_f32 v[54:55], v[62:63], v[54:55]
	v_pk_mul_f32 v[50:51], v[58:59], v[50:51]
	v_pk_mul_f32 v[48:49], v[56:57], v[48:49]
	v_pk_mul_f32 v[36:37], v[44:45], v[36:37]
	v_pk_mul_f32 v[38:39], v[46:47], v[38:39]
	v_pk_mul_f32 v[34:35], v[42:43], v[34:35]
	v_pk_mul_f32 v[32:33], v[40:41], v[32:33]
	v_pk_mul_f32 v[20:21], v[28:29], v[20:21]
	v_pk_mul_f32 v[22:23], v[30:31], v[22:23]
	v_pk_mul_f32 v[18:19], v[26:27], v[18:19]
	v_pk_mul_f32 v[16:17], v[24:25], v[16:17]
	v_pk_mul_f32 v[4:5], v[12:13], v[4:5]
	v_pk_mul_f32 v[6:7], v[14:15], v[6:7]
	v_pk_mul_f32 v[2:3], v[10:11], v[2:3]
	v_pk_mul_f32 v[0:1], v[8:9], v[0:1]
	s_andn2_b64 vcc, exec, s[4:5]
	s_mov_b64 s[4:5], -1
	s_cmp_lg_u32 s32, 0
	s_cbranch_scc1 .Lrc_b0
	s_waitcnt vmcnt(0)
	v_add_f32_e32 v172, v172, v173
	v_add_f32_e32 v174, v174, v175
	v_add_f32_e32 v176, v176, v177
	v_add_f32_e32 v178, v178, v179
	v_add_f32_e32 v180, v180, v181
	v_add_f32_e32 v182, v182, v183
	v_add_f32_e32 v184, v184, v185
	v_add_f32_e32 v186, v186, v187
	v_add_f32_e32 v188, v188, v189
	v_add_f32_e32 v190, v190, v191
	v_add_f32_e32 v218, v218, v219
	v_add_f32_e32 v220, v220, v221
	v_add_f32_e32 v222, v222, v223
	v_add_f32_e32 v224, v224, v225
	v_add_f32_e32 v226, v226, v227
	v_add_f32_e32 v228, v228, v229
	v_add_f32_e32 v172, v172, v174
	v_add_f32_e32 v176, v176, v178
	v_add_f32_e32 v180, v180, v182
	v_add_f32_e32 v184, v184, v186
	v_add_f32_e32 v188, v188, v190
	v_add_f32_e32 v218, v218, v220
	v_add_f32_e32 v222, v222, v224
	v_add_f32_e32 v226, v226, v228
	ds_bpermute_b32 v173, v202, v172
	ds_bpermute_b32 v177, v202, v176
	ds_bpermute_b32 v181, v202, v180
	ds_bpermute_b32 v185, v202, v184
	ds_bpermute_b32 v189, v202, v188
	ds_bpermute_b32 v219, v202, v218
	ds_bpermute_b32 v223, v202, v222
	ds_bpermute_b32 v227, v202, v226
	s_waitcnt lgkmcnt(0)
	v_add_f32_e32 v172, v172, v173
	v_add_f32_e32 v176, v176, v177
	v_add_f32_e32 v180, v180, v181
	v_add_f32_e32 v184, v184, v185
	v_add_f32_e32 v188, v188, v189
	v_add_f32_e32 v218, v218, v219
	v_add_f32_e32 v222, v222, v223
	v_add_f32_e32 v226, v226, v227
	ds_bpermute_b32 v173, v214, v172
	ds_bpermute_b32 v177, v214, v176
	ds_bpermute_b32 v181, v214, v180
	ds_bpermute_b32 v185, v214, v184
	ds_bpermute_b32 v189, v214, v188
	ds_bpermute_b32 v219, v214, v218
	ds_bpermute_b32 v223, v214, v222
	ds_bpermute_b32 v227, v214, v226
	s_waitcnt lgkmcnt(0)
	v_add_f32_e32 v172, v172, v173
	v_add_f32_e32 v176, v176, v177
	v_add_f32_e32 v180, v180, v181
	v_add_f32_e32 v184, v184, v185
	v_add_f32_e32 v188, v188, v189
	v_add_f32_e32 v218, v218, v219
	v_add_f32_e32 v222, v222, v223
	v_add_f32_e32 v226, v226, v227
	v_fmamk_f32 v172, v172, 0x3a800000, v212
	v_fmamk_f32 v176, v176, 0x3a800000, v212
	v_fmamk_f32 v180, v180, 0x3a800000, v212
	v_fmamk_f32 v184, v184, 0x3a800000, v212
	v_fmamk_f32 v188, v188, 0x3a800000, v212
	v_fmamk_f32 v218, v218, 0x3a800000, v212
	v_fmamk_f32 v222, v222, 0x3a800000, v212
	v_fmamk_f32 v226, v226, 0x3a800000, v212
	v_rsq_f32_e32 v236, v172
	v_rsq_f32_e32 v237, v176
	v_rsq_f32_e32 v238, v180
	v_rsq_f32_e32 v239, v184
	v_rsq_f32_e32 v240, v188
	v_rsq_f32_e32 v241, v218
	v_rsq_f32_e32 v252, v222
	v_rsq_f32_e32 v253, v226
	s_nop 0
	s_mov_b32 s32, 1
; __device__ __forceinline__ v4u pack8(const f32x4 a, const f32x4 b) { v4u w; w.x = cvt_pk_bf16(a[0], a[1]); w.y = cvt_pk_bf16(a[2], a[3]); w.z = cvt_pk_bf16(b[0], b[1]); w.w = cvt_pk_bf16(b[2], b[3]); return w; }
;     __device__ __forceinline__ void operator()(const f32x4 (&acc)[2][2][4][2], const pg8::Unit& u, int wr, int wc, int fr, int fq) const {
;     ...
;         for (int ai = 0; ai < 2; ++ai) { float rsv[4]; row_rstd4(ssq, row0 + ai * 128, fq, rsv);
; #pragma unroll
;             for (int m = 0; m < 4; ++m) {
;                 const int row = row0 + ai * 128 + m * 16; const float rs = rsv[m], c = -rs * LOG2E, rs2 = rs * rs;
;                 f32x4 e0 = acc[ai][0][m][0] * c, e1 = acc[ai][0][m][1] * c;
; #pragma unroll
;                 for (int i = 0; i < 4; ++i) { e0[i] = __builtin_amdgcn_exp2f(e0[i]); e1[i] = __builtin_amdgcn_exp2f(e1[i]); }
;                 e0 = e0 + 1.0f; e1 = e1 + 1.0f;
; #pragma unroll
;                 for (int i = 0; i < 4; ++i) { e0[i] = __builtin_amdgcn_rcpf(e0[i]); e1[i] = __builtin_amdgcn_rcpf(e1[i]); }
;                 const f32x4 h0 = (acc[ai][0][m][0] * acc[ai][1][m][0]) * rs2 * e0, h1 = (acc[ai][0][m][1] * acc[ai][1][m][1]) * rs2 * e1;
;                 *(v4u*)(O + (size_t)row * FFH + col0) = pack8(h0, h1);
.Lrc_b0:
	s_waitcnt lgkmcnt(0)
	s_waitcnt lgkmcnt(0)
	s_waitcnt lgkmcnt(0)
	s_waitcnt lgkmcnt(0)
	s_waitcnt lgkmcnt(0)
	s_waitcnt lgkmcnt(0)
	s_waitcnt lgkmcnt(0)
	s_waitcnt lgkmcnt(0)
	s_waitcnt lgkmcnt(0)
	v_mov_b32_e32 v145, v236
	v_mov_b32_e32 v153, v239
	v_mov_b32_e32 v155, v238
	v_mul_f32_e32 v152, 0xbfb8aa3b, v145
	v_pk_mul_f32 v[118:119], v[118:119], v[152:153] op_sel_hi:[1,0]
	v_pk_mul_f32 v[116:117], v[116:117], v[152:153] op_sel_hi:[1,0]
	v_pk_mul_f32 v[112:113], v[112:113], v[152:153] op_sel_hi:[1,0]
	v_pk_mul_f32 v[114:115], v[114:115], v[152:153] op_sel_hi:[1,0]
	v_exp_f32_e32 v116, v116
	v_exp_f32_e32 v112, v112
	v_exp_f32_e32 v117, v117
	v_exp_f32_e32 v118, v118
	v_exp_f32_e32 v119, v119
	v_exp_f32_e32 v113, v113
	v_exp_f32_e32 v114, v114
	v_exp_f32_e32 v115, v115
	v_pk_add_f32 v[118:119], v[118:119], 1.0 op_sel_hi:[1,0]
	v_pk_add_f32 v[116:117], v[116:117], 1.0 op_sel_hi:[1,0]
	v_pk_add_f32 v[112:113], v[112:113], 1.0 op_sel_hi:[1,0]
	v_pk_add_f32 v[114:115], v[114:115], 1.0 op_sel_hi:[1,0]
	v_rcp_f32_e32 v116, v116
	v_rcp_f32_e32 v112, v112
	v_rcp_f32_e32 v117, v117
	v_rcp_f32_e32 v118, v118
	v_rcp_f32_e32 v119, v119
	v_rcp_f32_e32 v113, v113
	v_rcp_f32_e32 v114, v114
	v_rcp_f32_e32 v115, v115
	v_mul_f32_e32 v154, v145, v145
	v_pk_mul_f32 v[124:125], v[124:125], v[154:155] op_sel_hi:[1,0]
	v_pk_mul_f32 v[126:127], v[126:127], v[154:155] op_sel_hi:[1,0]
	v_pk_mul_f32 v[120:121], v[120:121], v[154:155] op_sel_hi:[1,0]
	v_mov_b32_e32 v147, v237
	v_pk_mul_f32 v[122:123], v[122:123], v[154:155] op_sel_hi:[1,0]
	v_pk_mul_f32 v[118:119], v[126:127], v[118:119]
	v_pk_mul_f32 v[116:117], v[124:125], v[116:117]
	v_pk_mul_f32 v[112:113], v[120:121], v[112:113]
	v_pk_mul_f32 v[114:115], v[122:123], v[114:115]
	v_cvt_pk_bf16_f32 v116, v116, v117
	v_cvt_pk_bf16_f32 v117, v118, v119
	v_cvt_pk_bf16_f32 v118, v112, v113
	v_mov_b64_e32 v[112:113], s[12:13]
	v_cvt_pk_bf16_f32 v119, v114, v115
	v_mad_i64_i32 v[120:121], s[8:9], v140, s3, v[112:113]
	v_lshlrev_b64 v[114:115], 1, v[168:169]
	v_lshl_add_u64 v[120:121], v[120:121], 0, v[114:115]
	global_store_dwordx4 v[120:121], v[116:119], off
	v_mul_f32_e32 v124, v147, v147
	v_pk_mul_f32 v[100:101], v[100:101], v[124:125] op_sel_hi:[1,0]
	v_mul_f32_e32 v116, 0xbfb8aa3b, v147
	v_pk_mul_f32 v[120:121], v[108:109], v[116:117] op_sel_hi:[1,0]
	v_pk_mul_f32 v[118:119], v[110:111], v[116:117] op_sel_hi:[1,0]
	v_pk_mul_f32 v[122:123], v[106:107], v[116:117] op_sel_hi:[1,0]
	v_pk_mul_f32 v[116:117], v[104:105], v[116:117] op_sel_hi:[1,0]
	v_exp_f32_e32 v120, v120
	v_exp_f32_e32 v121, v121
	v_exp_f32_e32 v116, v116
	v_exp_f32_e32 v118, v118
	v_exp_f32_e32 v119, v119
	v_exp_f32_e32 v122, v122
	v_exp_f32_e32 v123, v123
	v_exp_f32_e32 v117, v117
	v_pk_add_f32 v[120:121], v[120:121], 1.0 op_sel_hi:[1,0]
	v_pk_add_f32 v[118:119], v[118:119], 1.0 op_sel_hi:[1,0]
	v_pk_add_f32 v[122:123], v[122:123], 1.0 op_sel_hi:[1,0]
	v_pk_add_f32 v[116:117], v[116:117], 1.0 op_sel_hi:[1,0]
	v_rcp_f32_e32 v120, v120
	v_rcp_f32_e32 v121, v121
	v_rcp_f32_e32 v116, v116
	v_rcp_f32_e32 v117, v117
	v_rcp_f32_e32 v118, v118
	v_rcp_f32_e32 v122, v122
	v_rcp_f32_e32 v119, v119
	v_rcp_f32_e32 v123, v123
	v_pk_mul_f32 v[102:103], v[102:103], v[124:125] op_sel_hi:[1,0]
	v_pk_mul_f32 v[100:101], v[100:101], v[120:121]
	v_pk_mul_f32 v[96:97], v[96:97], v[124:125] op_sel_hi:[1,0]
	v_pk_mul_f32 v[98:99], v[98:99], v[124:125] op_sel_hi:[1,0]
	v_pk_mul_f32 v[102:103], v[102:103], v[118:119]
	v_pk_mul_f32 v[104:105], v[98:99], v[122:123]
	v_pk_mul_f32 v[98:99], v[96:97], v[116:117]
	v_cvt_pk_bf16_f32 v96, v100, v101
	v_mad_i64_i32 v[100:101], s[8:9], v146, s3, v[112:113]
	v_cvt_pk_bf16_f32 v97, v102, v103
	v_cvt_pk_bf16_f32 v98, v98, v99
	v_cvt_pk_bf16_f32 v99, v104, v105
	v_lshl_add_u64 v[100:101], v[100:101], 0, v[114:115]
	global_store_dwordx4 v[100:101], v[96:99], off
	v_mul_f32_e32 v104, v155, v155
	v_pk_mul_f32 v[84:85], v[84:85], v[104:105] op_sel_hi:[1,0]
	v_mul_f32_e32 v96, 0xbfb8aa3b, v155
	v_pk_mul_f32 v[100:101], v[92:93], v[96:97] op_sel_hi:[1,0]
	v_pk_mul_f32 v[98:99], v[94:95], v[96:97] op_sel_hi:[1,0]
	v_pk_mul_f32 v[102:103], v[90:91], v[96:97] op_sel_hi:[1,0]
	v_pk_mul_f32 v[96:97], v[88:89], v[96:97] op_sel_hi:[1,0]
	v_exp_f32_e32 v100, v100
	v_exp_f32_e32 v101, v101
	v_exp_f32_e32 v96, v96
	v_exp_f32_e32 v98, v98
	v_exp_f32_e32 v99, v99
	v_exp_f32_e32 v102, v102
	v_exp_f32_e32 v103, v103
	v_exp_f32_e32 v97, v97
	v_pk_add_f32 v[100:101], v[100:101], 1.0 op_sel_hi:[1,0]
	v_pk_add_f32 v[98:99], v[98:99], 1.0 op_sel_hi:[1,0]
	v_pk_add_f32 v[102:103], v[102:103], 1.0 op_sel_hi:[1,0]
	v_pk_add_f32 v[96:97], v[96:97], 1.0 op_sel_hi:[1,0]
	v_rcp_f32_e32 v100, v100
	v_rcp_f32_e32 v101, v101
	v_rcp_f32_e32 v96, v96
	v_rcp_f32_e32 v97, v97
	v_rcp_f32_e32 v98, v98
	v_rcp_f32_e32 v102, v102
	v_rcp_f32_e32 v99, v99
	v_rcp_f32_e32 v103, v103
	v_pk_mul_f32 v[86:87], v[86:87], v[104:105] op_sel_hi:[1,0]
	v_pk_mul_f32 v[84:85], v[84:85], v[100:101]
	v_pk_mul_f32 v[80:81], v[80:81], v[104:105] op_sel_hi:[1,0]
	v_pk_mul_f32 v[82:83], v[82:83], v[104:105] op_sel_hi:[1,0]
	v_pk_mul_f32 v[86:87], v[86:87], v[98:99]
	v_pk_mul_f32 v[88:89], v[82:83], v[102:103]
	v_pk_mul_f32 v[82:83], v[80:81], v[96:97]
	v_cvt_pk_bf16_f32 v80, v84, v85
	v_mad_i64_i32 v[84:85], s[8:9], v144, s3, v[112:113]
	v_cvt_pk_bf16_f32 v81, v86, v87
	v_cvt_pk_bf16_f32 v82, v82, v83
	v_cvt_pk_bf16_f32 v83, v88, v89
	v_lshl_add_u64 v[84:85], v[84:85], 0, v[114:115]
	global_store_dwordx4 v[84:85], v[80:83], off
	v_mul_f32_e32 v88, v153, v153
	v_pk_mul_f32 v[68:69], v[68:69], v[88:89] op_sel_hi:[1,0]
	v_mul_f32_e32 v80, 0xbfb8aa3b, v153
	v_pk_mul_f32 v[84:85], v[76:77], v[80:81] op_sel_hi:[1,0]
; __device__ __forceinline__ v4u pack8(const f32x4 a, const f32x4 b) { v4u w; w.x = cvt_pk_bf16(a[0], a[1]); w.y = cvt_pk_bf16(a[2], a[3]); w.z = cvt_pk_bf16(b[0], b[1]); w.w = cvt_pk_bf16(b[2], b[3]); return w; }
; __device__ __forceinline__ void row_rstd4(const float* ssq, int row0, int fq, float (&rs)[4]) {
;     f32x4 v[4];
; #pragma unroll
;     for (int m = 0; m < 4; ++m) v[m] = *(const f32x4*)(ssq + (size_t)(row0 + m * 16) * 16 + fq * 4);
; #pragma unroll
;     for (int m = 0; m < 4; ++m) { float t = (v[m][0] + v[m][1]) + (v[m][2] + v[m][3]); t += __shfl_xor(t, 16); t += __shfl_xor(t, 32); rs[m] = __builtin_amdgcn_rsqf(t * (1.f / DM) + EPS); }
; }
;     __device__ __forceinline__ void operator()(const f32x4 (&acc)[2][2][4][2], const pg8::Unit& u, int wr, int wc, int fr, int fq) const {
;     ...
;                 const int row = row0 + ai * 128 + m * 16; const float rs = rsv[m], c = -rs * LOG2E, rs2 = rs * rs;
;                 f32x4 e0 = acc[ai][0][m][0] * c, e1 = acc[ai][0][m][1] * c;
; #pragma unroll
;                 for (int i = 0; i < 4; ++i) { e0[i] = __builtin_amdgcn_exp2f(e0[i]); e1[i] = __builtin_amdgcn_exp2f(e1[i]); }
;                 e0 = e0 + 1.0f; e1 = e1 + 1.0f;
; #pragma unroll
;                 for (int i = 0; i < 4; ++i) { e0[i] = __builtin_amdgcn_rcpf(e0[i]); e1[i] = __builtin_amdgcn_rcpf(e1[i]); }
;                 const f32x4 h0 = (acc[ai][0][m][0] * acc[ai][1][m][0]) * rs2 * e0, h1 = (acc[ai][0][m][1] * acc[ai][1][m][1]) * rs2 * e1;
;                 *(v4u*)(O + (size_t)row * FFH + col0) = pack8(h0, h1);
	v_pk_mul_f32 v[82:83], v[78:79], v[80:81] op_sel_hi:[1,0]
	v_pk_mul_f32 v[86:87], v[74:75], v[80:81] op_sel_hi:[1,0]
	v_pk_mul_f32 v[80:81], v[72:73], v[80:81] op_sel_hi:[1,0]
	v_exp_f32_e32 v84, v84
	v_exp_f32_e32 v85, v85
	v_exp_f32_e32 v80, v80
	v_exp_f32_e32 v82, v82
	v_exp_f32_e32 v83, v83
	v_exp_f32_e32 v86, v86
	v_exp_f32_e32 v87, v87
	v_exp_f32_e32 v81, v81
	v_pk_add_f32 v[84:85], v[84:85], 1.0 op_sel_hi:[1,0]
	v_pk_add_f32 v[82:83], v[82:83], 1.0 op_sel_hi:[1,0]
	v_pk_add_f32 v[86:87], v[86:87], 1.0 op_sel_hi:[1,0]
	v_pk_add_f32 v[80:81], v[80:81], 1.0 op_sel_hi:[1,0]
	v_rcp_f32_e32 v84, v84
	v_rcp_f32_e32 v85, v85
	v_rcp_f32_e32 v80, v80
	v_rcp_f32_e32 v81, v81
	v_rcp_f32_e32 v82, v82
	v_rcp_f32_e32 v86, v86
	v_rcp_f32_e32 v83, v83
	v_rcp_f32_e32 v87, v87
	v_pk_mul_f32 v[70:71], v[70:71], v[88:89] op_sel_hi:[1,0]
	v_pk_mul_f32 v[68:69], v[68:69], v[84:85]
	v_pk_mul_f32 v[64:65], v[64:65], v[88:89] op_sel_hi:[1,0]
	v_pk_mul_f32 v[66:67], v[66:67], v[88:89] op_sel_hi:[1,0]
	v_pk_mul_f32 v[70:71], v[70:71], v[82:83]
	v_pk_mul_f32 v[72:73], v[66:67], v[86:87]
	v_pk_mul_f32 v[66:67], v[64:65], v[80:81]
	v_cvt_pk_bf16_f32 v64, v68, v69
	v_mad_i64_i32 v[68:69], s[8:9], v142, s3, v[112:113]
	v_add_u32_e32 v84, 0x80, v140
	v_cvt_pk_bf16_f32 v65, v70, v71
	v_cvt_pk_bf16_f32 v66, v66, v67
	v_cvt_pk_bf16_f32 v67, v72, v73
	v_lshl_add_u64 v[68:69], v[68:69], 0, v[114:115]
	v_ashrrev_i32_e32 v85, 31, v84
	global_store_dwordx4 v[68:69], v[64:67], off
	v_add_u32_e32 v86, 0x90, v140
	v_ashrrev_i32_e32 v87, 31, v86
	v_add_u32_e32 v66, 0xa0, v140
	v_add_u32_e32 v64, 0xb0, v140
	v_ashrrev_i32_e32 v65, 31, v64
	v_lshlrev_b64 v[80:81], 6, v[64:65]
	v_lshl_add_u64 v[80:81], v[134:135], 0, v[80:81]
	s_waitcnt lgkmcnt(0)
	s_nop 0
	s_waitcnt lgkmcnt(0)
	s_waitcnt lgkmcnt(0)
	s_waitcnt lgkmcnt(0)
	s_waitcnt lgkmcnt(0)
	s_waitcnt lgkmcnt(0)
	s_waitcnt lgkmcnt(0)
	v_mov_b32_e32 v65, v240
	s_waitcnt lgkmcnt(0)
	s_waitcnt lgkmcnt(0)
; __device__ __forceinline__ v4u pack8(const f32x4 a, const f32x4 b) { v4u w; w.x = cvt_pk_bf16(a[0], a[1]); w.y = cvt_pk_bf16(a[2], a[3]); w.z = cvt_pk_bf16(b[0], b[1]); w.w = cvt_pk_bf16(b[2], b[3]); return w; }
;     __device__ __forceinline__ void operator()(const f32x4 (&acc)[2][2][4][2], const pg8::Unit& u, int wr, int wc, int fr, int fq) const {
;     ...
;                 const int row = row0 + ai * 128 + m * 16; const float rs = rsv[m], c = -rs * LOG2E, rs2 = rs * rs;
;                 f32x4 e0 = acc[ai][0][m][0] * c, e1 = acc[ai][0][m][1] * c;
; #pragma unroll
;                 for (int i = 0; i < 4; ++i) { e0[i] = __builtin_amdgcn_exp2f(e0[i]); e1[i] = __builtin_amdgcn_exp2f(e1[i]); }
;                 e0 = e0 + 1.0f; e1 = e1 + 1.0f;
; #pragma unroll
;                 for (int i = 0; i < 4; ++i) { e0[i] = __builtin_amdgcn_rcpf(e0[i]); e1[i] = __builtin_amdgcn_rcpf(e1[i]); }
;                 const f32x4 h0 = (acc[ai][0][m][0] * acc[ai][1][m][0]) * rs2 * e0, h1 = (acc[ai][0][m][1] * acc[ai][1][m][1]) * rs2 * e1;
;                 *(v4u*)(O + (size_t)row * FFH + col0) = pack8(h0, h1);
	v_mov_b32_e32 v78, v253
	v_mul_f32_e32 v68, 0xbfb8aa3b, v65
	v_pk_mul_f32 v[72:73], v[60:61], v[68:69] op_sel_hi:[1,0]
	v_mov_b32_e32 v77, v252
	v_pk_mul_f32 v[70:71], v[62:63], v[68:69] op_sel_hi:[1,0]
	v_pk_mul_f32 v[74:75], v[58:59], v[68:69] op_sel_hi:[1,0]
	v_pk_mul_f32 v[68:69], v[56:57], v[68:69] op_sel_hi:[1,0]
	v_exp_f32_e32 v72, v72
	v_exp_f32_e32 v73, v73
	v_exp_f32_e32 v68, v68
	v_exp_f32_e32 v70, v70
	v_exp_f32_e32 v71, v71
	v_exp_f32_e32 v74, v74
	v_exp_f32_e32 v75, v75
	v_exp_f32_e32 v69, v69
	v_pk_add_f32 v[72:73], v[72:73], 1.0 op_sel_hi:[1,0]
	v_pk_add_f32 v[70:71], v[70:71], 1.0 op_sel_hi:[1,0]
	v_pk_add_f32 v[74:75], v[74:75], 1.0 op_sel_hi:[1,0]
	v_pk_add_f32 v[68:69], v[68:69], 1.0 op_sel_hi:[1,0]
	v_rcp_f32_e32 v72, v72
	v_rcp_f32_e32 v73, v73
	v_rcp_f32_e32 v68, v68
	v_rcp_f32_e32 v69, v69
	v_rcp_f32_e32 v70, v70
	v_rcp_f32_e32 v74, v74
	v_rcp_f32_e32 v71, v71
	v_rcp_f32_e32 v75, v75
	v_mul_f32_e32 v76, v65, v65
	v_mov_b32_e32 v67, v241
	v_pk_mul_f32 v[52:53], v[52:53], v[76:77] op_sel_hi:[1,0]
	v_pk_mul_f32 v[54:55], v[54:55], v[76:77] op_sel_hi:[1,0]
	v_pk_mul_f32 v[52:53], v[52:53], v[72:73]
	v_pk_mul_f32 v[48:49], v[48:49], v[76:77] op_sel_hi:[1,0]
	v_pk_mul_f32 v[50:51], v[50:51], v[76:77] op_sel_hi:[1,0]
	v_pk_mul_f32 v[54:55], v[54:55], v[70:71]
	v_pk_mul_f32 v[56:57], v[50:51], v[74:75]
	v_pk_mul_f32 v[50:51], v[48:49], v[68:69]
	v_cvt_pk_bf16_f32 v48, v52, v53
	v_mad_i64_i32 v[52:53], s[8:9], v84, s3, v[112:113]
	v_cvt_pk_bf16_f32 v49, v54, v55
	v_cvt_pk_bf16_f32 v50, v50, v51
	v_cvt_pk_bf16_f32 v51, v56, v57
	v_lshl_add_u64 v[52:53], v[52:53], 0, v[114:115]
	global_store_dwordx4 v[52:53], v[48:51], off
	v_mul_f32_e32 v56, v67, v67
	v_pk_mul_f32 v[36:37], v[36:37], v[56:57] op_sel_hi:[1,0]
	v_mul_f32_e32 v48, 0xbfb8aa3b, v67
	v_pk_mul_f32 v[52:53], v[44:45], v[48:49] op_sel_hi:[1,0]
	v_pk_mul_f32 v[50:51], v[46:47], v[48:49] op_sel_hi:[1,0]
	v_pk_mul_f32 v[54:55], v[42:43], v[48:49] op_sel_hi:[1,0]
	v_pk_mul_f32 v[48:49], v[40:41], v[48:49] op_sel_hi:[1,0]
	v_exp_f32_e32 v52, v52
	v_exp_f32_e32 v53, v53
	v_exp_f32_e32 v48, v48
	v_exp_f32_e32 v50, v50
	v_exp_f32_e32 v51, v51
	v_exp_f32_e32 v54, v54
	v_exp_f32_e32 v55, v55
	v_exp_f32_e32 v49, v49
	v_pk_add_f32 v[52:53], v[52:53], 1.0 op_sel_hi:[1,0]
	v_pk_add_f32 v[50:51], v[50:51], 1.0 op_sel_hi:[1,0]
	v_pk_add_f32 v[54:55], v[54:55], 1.0 op_sel_hi:[1,0]
	v_pk_add_f32 v[48:49], v[48:49], 1.0 op_sel_hi:[1,0]
	v_rcp_f32_e32 v52, v52
	v_rcp_f32_e32 v53, v53
	v_rcp_f32_e32 v48, v48
	v_rcp_f32_e32 v49, v49
	v_rcp_f32_e32 v50, v50
	v_rcp_f32_e32 v54, v54
	v_rcp_f32_e32 v51, v51
	v_rcp_f32_e32 v55, v55
	v_pk_mul_f32 v[38:39], v[38:39], v[56:57] op_sel_hi:[1,0]
	v_pk_mul_f32 v[36:37], v[36:37], v[52:53]
	v_pk_mul_f32 v[32:33], v[32:33], v[56:57] op_sel_hi:[1,0]
	v_pk_mul_f32 v[34:35], v[34:35], v[56:57] op_sel_hi:[1,0]
	v_pk_mul_f32 v[38:39], v[38:39], v[50:51]
	v_pk_mul_f32 v[40:41], v[34:35], v[54:55]
	v_pk_mul_f32 v[34:35], v[32:33], v[48:49]
	v_cvt_pk_bf16_f32 v32, v36, v37
	v_mad_i64_i32 v[36:37], s[8:9], v86, s3, v[112:113]
	v_cvt_pk_bf16_f32 v33, v38, v39
	v_cvt_pk_bf16_f32 v34, v34, v35
	v_cvt_pk_bf16_f32 v35, v40, v41
	v_lshl_add_u64 v[36:37], v[36:37], 0, v[114:115]
	global_store_dwordx4 v[36:37], v[32:35], off
	v_mul_f32_e32 v40, v77, v77
	v_pk_mul_f32 v[20:21], v[20:21], v[40:41] op_sel_hi:[1,0]
	v_mul_f32_e32 v32, 0xbfb8aa3b, v77
	v_pk_mul_f32 v[36:37], v[28:29], v[32:33] op_sel_hi:[1,0]
	v_pk_mul_f32 v[34:35], v[30:31], v[32:33] op_sel_hi:[1,0]
	v_pk_mul_f32 v[38:39], v[26:27], v[32:33] op_sel_hi:[1,0]
	v_pk_mul_f32 v[32:33], v[24:25], v[32:33] op_sel_hi:[1,0]
	v_exp_f32_e32 v36, v36
	v_exp_f32_e32 v37, v37
	v_exp_f32_e32 v32, v32
	v_exp_f32_e32 v34, v34
	v_exp_f32_e32 v35, v35
	v_exp_f32_e32 v38, v38
	v_exp_f32_e32 v39, v39
	v_exp_f32_e32 v33, v33
	v_pk_add_f32 v[36:37], v[36:37], 1.0 op_sel_hi:[1,0]
	v_pk_add_f32 v[34:35], v[34:35], 1.0 op_sel_hi:[1,0]
	v_pk_add_f32 v[38:39], v[38:39], 1.0 op_sel_hi:[1,0]
	v_pk_add_f32 v[32:33], v[32:33], 1.0 op_sel_hi:[1,0]
	v_rcp_f32_e32 v36, v36
	v_rcp_f32_e32 v37, v37
	v_rcp_f32_e32 v32, v32
	v_rcp_f32_e32 v33, v33
	v_rcp_f32_e32 v34, v34
	v_rcp_f32_e32 v38, v38
	v_rcp_f32_e32 v35, v35
	v_rcp_f32_e32 v39, v39
	v_pk_mul_f32 v[22:23], v[22:23], v[40:41] op_sel_hi:[1,0]
	v_pk_mul_f32 v[20:21], v[20:21], v[36:37]
	v_pk_mul_f32 v[16:17], v[16:17], v[40:41] op_sel_hi:[1,0]
	v_pk_mul_f32 v[18:19], v[18:19], v[40:41] op_sel_hi:[1,0]
	v_pk_mul_f32 v[22:23], v[22:23], v[34:35]
	v_pk_mul_f32 v[24:25], v[18:19], v[38:39]
	v_pk_mul_f32 v[18:19], v[16:17], v[32:33]
	v_cvt_pk_bf16_f32 v16, v20, v21
	v_mad_i64_i32 v[20:21], s[8:9], v66, s3, v[112:113]
	v_cvt_pk_bf16_f32 v17, v22, v23
	v_cvt_pk_bf16_f32 v18, v18, v19
	v_cvt_pk_bf16_f32 v19, v24, v25
	v_lshl_add_u64 v[20:21], v[20:21], 0, v[114:115]
	global_store_dwordx4 v[20:21], v[16:19], off
	v_mul_f32_e32 v24, v78, v78
	v_pk_mul_f32 v[4:5], v[4:5], v[24:25] op_sel_hi:[1,0]
	v_mul_f32_e32 v16, 0xbfb8aa3b, v78
	v_pk_mul_f32 v[20:21], v[12:13], v[16:17] op_sel_hi:[1,0]
	v_pk_mul_f32 v[18:19], v[14:15], v[16:17] op_sel_hi:[1,0]
	v_pk_mul_f32 v[22:23], v[10:11], v[16:17] op_sel_hi:[1,0]
	v_pk_mul_f32 v[16:17], v[8:9], v[16:17] op_sel_hi:[1,0]
	v_exp_f32_e32 v20, v20
	v_exp_f32_e32 v21, v21
	v_exp_f32_e32 v16, v16
	v_exp_f32_e32 v18, v18
	v_exp_f32_e32 v19, v19
	v_exp_f32_e32 v22, v22
	v_exp_f32_e32 v23, v23
	v_exp_f32_e32 v17, v17
	v_pk_add_f32 v[20:21], v[20:21], 1.0 op_sel_hi:[1,0]
	v_pk_add_f32 v[18:19], v[18:19], 1.0 op_sel_hi:[1,0]
	v_pk_add_f32 v[22:23], v[22:23], 1.0 op_sel_hi:[1,0]
	v_pk_add_f32 v[16:17], v[16:17], 1.0 op_sel_hi:[1,0]
	v_rcp_f32_e32 v20, v20
	v_rcp_f32_e32 v21, v21
	v_rcp_f32_e32 v16, v16
	v_rcp_f32_e32 v17, v17
	v_rcp_f32_e32 v18, v18
	v_rcp_f32_e32 v22, v22
	v_rcp_f32_e32 v19, v19
	v_rcp_f32_e32 v23, v23
	v_pk_mul_f32 v[6:7], v[6:7], v[24:25] op_sel_hi:[1,0]
	v_pk_mul_f32 v[4:5], v[4:5], v[20:21]
	v_pk_mul_f32 v[0:1], v[0:1], v[24:25] op_sel_hi:[1,0]
	v_pk_mul_f32 v[2:3], v[2:3], v[24:25] op_sel_hi:[1,0]
	v_pk_mul_f32 v[6:7], v[6:7], v[18:19]
	v_pk_mul_f32 v[8:9], v[2:3], v[22:23]
	v_pk_mul_f32 v[2:3], v[0:1], v[16:17]
	v_cvt_pk_bf16_f32 v0, v4, v5
	v_mad_i64_i32 v[4:5], s[8:9], v64, s3, v[112:113]
	v_cvt_pk_bf16_f32 v1, v6, v7
	v_cvt_pk_bf16_f32 v2, v2, v3
	v_cvt_pk_bf16_f32 v3, v8, v9
	v_lshl_add_u64 v[4:5], v[4:5], 0, v[114:115]
	global_store_dwordx4 v[4:5], v[0:3], off
	s_cbranch_vccnz .LBB0_152
	s_andn2_b64 vcc, exec, s[10:11]
	s_cbranch_vccnz .LBB0_151
	s_barrier
	s_branch .LBB0_151

;     __host__ __device__ bool next(int i, Unit& u) const {
;         const long L = (long)i * G + c; if (L >= nwg) return false;
;         int wgid = (int)L; { const int q = nwg / NXCD, r = nwg % NXCD, xcd = wgid % NXCD, off = wgid / NXCD; wgid = (xcd < r ? xcd * (q + 1) : r * (q + 1) + (xcd - r) * q) + off; }
;         const int nig = WGM * nN, gid = wgid / nig, fm = gid * WGM, gsz = (nM - fm) < WGM ? (nM - fm) : WGM;
;         u.pm = fm + ((wgid % nig) % gsz); u.pn = (wgid % nig) / gsz; return true;
;     }
; template <class Epi, class Sched, bool ALIGN_EPI = false, bool SP2 = false>
; __device__ __forceinline__ void gemm_phase(PG8_LAS unsigned char* lds, const Gemm g, const Sched& S, const Epi& E) {
;     int tid_ = threadIdx.x; asm volatile("" : "+v"(tid_)); const int tid = tid_, wid = __builtin_amdgcn_readfirstlane(tid >> 6), lane = tid & 63, wr = wid >> 2, wc = wid & 3, fr = lane & 15, fq = lane >> 4;
;     const int K = g.K, nt = K / BK;
;     unsigned voffA[2], voffB[2];
; #pragma unroll
;     for (int i = 0; i < 2; ++i) { int R, C; stage_rc(tid * 16 + i * 8192, R, C); const int Rb = Epi::PERM ? ((R & ~31) + perm32(R & 31)) : R;
;         voffA[i] = (unsigned)(R * g.lda + C) * 2u; voffB[i] = (unsigned)(Rb * g.ldb + C) * 2u; }
;     const size_t kstep = (size_t)(BK * 2);
;     const size_t hstepA = (size_t)HALF * g.lda * 2, hstepB = (size_t)HALF * g.ldb * 2;
;     const size_t tstepA = 2 * hstepA, tstepB = 2 * hstepB;
;     const unsigned ldsw = (unsigned)wid * 1024u;
;     const int aoff = lds_byte(wr * 64 + fr, fq * 8), boff = lds_byte(wc * 32 + fr, fq * 8);
;     ...
;     Unit cur, nxt; int ui = 0;
;     if (!S.next(0, cur)) return;
;     f32x4 acc[2][2][4][2];
; #pragma unroll
;     for (int a = 0; a < 2; ++a)
; #pragma unroll
;         for (int b = 0; b < 2; ++b)
; #pragma unroll
;             for (int m = 0; m < 4; ++m)
; #pragma unroll
;                 for (int n = 0; n < 2; ++n) acc[a][b][m][n] = (f32x4){0.f, 0.f, 0.f, 0.f};
;     bf16x8 At[4][2], B0[2][2], B1[2][2];
;     const char* cA = (const char*)g.A + S.aoff(cur, tstepA); const char* cB = (const char*)g.Bt + S.boff(cur, tstepB);
;     S.a_ready(cur);
;     if constexpr (SP2) {
;         PG8_STAGE(PG8_SB(0, 0), cB, voffB); PG8_STAGE(PG8_SB(0, 1), cB + hstepB, voffB); PG8_STAGE(PG8_SA(0, 0), cA, voffA); PG8_STAGE(PG8_SA(0, 1), cA + hstepA, voffA);
;         if (wr == 1) PG8_BAR;
.LBB0_1212:
	s_add_i32 s101, s101, 1
	s_mov_b32 s32, 0
	v_readlane_b32 s8, v255, 20
	v_readlane_b32 s9, v255, 21
	v_readlane_b32 s10, v255, 22
	v_readlane_b32 s11, v255, 23
	s_mov_b32 s0, s83
	s_mov_b32 s1, s56
	s_mov_b32 s12, s69
	s_mov_b64 s[4:5], s[10:11]
	s_mov_b64 s[6:7], s[8:9]
	v_mov_b32_e32 v14, v203
	s_waitcnt lgkmcnt(0)
	s_barrier
	s_cmpk_gt_i32 s0, 0x57f
	v_readfirstlane_b32 s10, v14
	s_cbranch_scc1 .LBB0_1228
	v_lshlrev_b32_e32 v0, 4, v14
	v_add_u32_e32 v1, 0x2000, v0
	v_ashrrev_i32_e32 v2, 31, v1
	v_lshrrev_b32_e32 v2, 22, v2
	v_add_u32_e32 v2, v1, v2
	v_ashrrev_i32_e32 v8, 10, v2
	v_mul_i32_i24_e32 v2, 0x400, v8
	v_sub_u32_e32 v1, v1, v2
	v_lshrrev_b32_e32 v2, 4, v1
	v_bitop3_b32 v1, v2, v1, 32 bitop3:0x6c
	v_ashrrev_i32_e32 v2, 31, v1
	v_lshrrev_b32_e32 v2, 26, v2
	v_add_u32_e32 v2, v1, v2
	v_lshlrev_b32_e32 v3, 3, v8
	v_ashrrev_i32_e32 v9, 6, v2
	v_and_b32_e32 v3, -16, v3
	v_add_u32_e32 v3, v9, v3
	v_and_b32_e32 v4, 3, v9
	s_mov_b32 s6, 0x1fffe0
	v_lshrrev_b32_e32 v5, 2, v3
	v_lshlrev_b32_e32 v6, 1, v3
	v_and_b32_e32 v2, 0xc0, v2
	v_and_or_b32 v4, v3, s6, v4
	v_and_b32_e32 v5, 4, v5
	v_and_b32_e32 v6, 24, v6
	v_sub_u32_e32 v1, v1, v2
	v_or3_b32 v4, v4, v5, v6
	v_lshlrev_b32_e32 v5, 5, v8
	v_ashrrev_i16_sdwa v1, v244, sext(v1) dst_sel:DWORD dst_unused:UNUSED_PAD src0_sel:DWORD src1_sel:BYTE_0
	v_and_b32_e32 v5, 32, v5
	v_bfe_i32 v10, v1, 0, 16
	v_add_lshl_u32 v1, v5, v10, 1
	v_lshl_add_u32 v128, v4, 11, v1
	v_lshl_add_u32 v130, v3, 11, v1
	v_bfe_i32 v1, v14, 27, 1
	v_lshrrev_b32_e32 v1, 22, v1
	v_add_u32_e32 v1, v0, v1
	v_and_b32_e32 v1, 0xfffffc00, v1
	v_sub_u32_e32 v0, v0, v1
	v_lshrrev_b32_e32 v1, 4, v0
	v_ashrrev_i32_e32 v2, 31, v14
	v_bitop3_b32 v0, v1, v0, 32 bitop3:0x6c
	v_lshrrev_b32_e32 v2, 26, v2
	v_ashrrev_i32_e32 v1, 31, v0
	v_add_u32_e32 v2, v14, v2
	s_add_u32 s28, s4, 0x3a00000
	v_lshrrev_b32_e32 v1, 26, v1
	v_ashrrev_i32_e32 v12, 6, v2
	s_addc_u32 s29, s5, 0
	v_add_u32_e32 v1, v0, v1
	v_lshlrev_b32_e32 v2, 3, v12
	s_add_u32 s30, s4, 0x2200000
	v_ashrrev_i32_e32 v11, 6, v1
	v_and_b32_e32 v2, -16, v2
	s_addc_u32 s31, s5, 0
	v_add_u32_e32 v2, v11, v2
	v_and_b32_e32 v3, 3, v11
	s_ashr_i32 s34, s0, 31
	v_and_or_b32 v3, v2, s6, v3
	s_lshr_b32 s6, s34, 29
	s_add_i32 s6, s0, s6
	s_ashr_i32 s13, s10, 6
	s_ashr_i32 s7, s6, 3
	s_and_b32 s6, s6, -8
	s_ashr_i32 s2, s10, 8
	s_lshl_b32 s11, s13, 10
	s_sub_i32 s6, s0, s6
	s_cmp_lt_i32 s6, 0
	s_movk_i32 s8, 0xb1
	s_cselect_b32 s8, s8, 0xb0
	s_mul_i32 s6, s6, s8
	s_add_i32 s6, s6, s7
	s_mul_hi_i32 s7, s6, 0x2e8ba2e9
	s_lshr_b32 s8, s7, 31
	s_ashr_i32 s7, s7, 5
	s_add_i32 s7, s7, s8
	s_lshl_b32 s9, s7, 3
	s_mulk_i32 s7, 0xb0
	s_sub_i32 s6, s6, s7
	s_bfe_u32 s7, s6, 0x3001c
	s_add_i32 s7, s6, s7
	s_sext_i32_i16 s8, s7
	s_and_b32 s7, s7, 0xfff8
	s_sub_i32 s6, s6, s7
	s_sext_i32_i16 s6, s6
	s_lshr_b32 s8, s8, 3
	s_add_i32 s20, s9, s6
	s_ashr_i32 s21, s20, 31
	s_bfe_i64 s[14:15], s[8:9], 0x100000
	s_lshl_b64 s[6:7], s[20:21], 19
	s_lshl_b64 s[14:15], s[14:15], 19
	s_add_u32 s22, s30, s14
	s_addc_u32 s23, s31, s15
	s_add_i32 s21, s12, 0x10000
	v_lshrrev_b32_e32 v4, 2, v2
	v_lshlrev_b32_e32 v5, 1, v2
	v_and_b32_e32 v1, 0xc0, v1
	s_add_i32 s35, s21, s11
	v_and_b32_e32 v4, 4, v4
	v_and_b32_e32 v5, 24, v5
	v_sub_u32_e32 v0, v0, v1
	s_add_i32 s36, s35, 0x2000
	v_or3_b32 v3, v3, v4, v5
	v_lshlrev_b32_e32 v4, 5, v12
	v_ashrrev_i16_sdwa v0, v244, sext(v0) dst_sel:DWORD dst_unused:UNUSED_PAD src0_sel:DWORD src1_sel:BYTE_0
	s_add_u32 s14, s22, 0x40000
	v_and_b32_e32 v4, 32, v4
	v_bfe_i32 v13, v0, 0, 16
	s_addc_u32 s15, s23, 0
	s_add_i32 s37, s12, 0x14000
	v_add_lshl_u32 v0, v4, v13, 1
	s_add_i32 s38, s37, s11
	v_lshl_add_u32 v192, v3, 11, v0
	s_mov_b32 m0, s35
	s_add_i32 s39, s38, 0x2000
	global_load_lds_dwordx4 v192, s[22:23]
	s_mov_b32 m0, s36
	s_add_u32 s24, s28, s6
	global_load_lds_dwordx4 v128, s[22:23]
	s_mov_b32 m0, s38
	s_addc_u32 s25, s29, s7
	s_add_i32 s40, s12, s11
	global_load_lds_dwordx4 v192, s[14:15]
	s_mov_b32 m0, s39
	s_add_i32 s41, s40, 0x2000
	v_lshl_add_u32 v132, v2, 11, v0
	global_load_lds_dwordx4 v128, s[14:15]
	s_mov_b32 m0, s40
	s_add_u32 s6, s24, 0x40000
	global_load_lds_dwordx4 v132, s[24:25]
	s_mov_b32 m0, s41
	s_addc_u32 s7, s25, 0
	s_add_i32 s42, s40, 0x4000
	global_load_lds_dwordx4 v130, s[24:25]
	s_mov_b32 m0, s42
	s_add_i32 s43, s40, 0x6000
	global_load_lds_dwordx4 v132, s[6:7]
	s_mov_b32 m0, s43
	v_mov_b32_e32 v129, v193
	global_load_lds_dwordx4 v130, s[6:7]
	v_mov_b32_e32 v133, v193
	v_mov_b32_e32 v131, v193
	s_cmp_eq_u32 s2, 1
	v_lshl_add_u64 v[6:7], s[22:23], 0, v[192:193]
	v_lshl_add_u64 v[4:5], s[22:23], 0, v[128:129]
	v_lshl_add_u64 v[0:1], s[24:25], 0, v[132:133]
	s_cselect_b64 s[6:7], -1, 0
	s_cmp_lg_u32 s2, 1
	v_lshl_add_u64 v[2:3], s[24:25], 0, v[130:131]
	s_cbranch_scc1 .LBB0_1215
	s_barrier

; __device__ __forceinline__ void row_rstd4(const float* ssq, int row0, int fq, float (&rs)[4]) {
;     f32x4 v[4];
; #pragma unroll
;     for (int m = 0; m < 4; ++m) v[m] = *(const f32x4*)(ssq + (size_t)(row0 + m * 16) * 16 + fq * 4);
; #pragma unroll
;     for (int m = 0; m < 4; ++m) { float t = (v[m][0] + v[m][1]) + (v[m][2] + v[m][3]); t += __shfl_xor(t, 16); t += __shfl_xor(t, 32); rs[m] = __builtin_amdgcn_rsqf(t * (1.f / DM) + EPS); }
; }
;     __device__ __forceinline__ void operator()(const f32x4 (&acc)[2][2][4][2], const pg8::Unit& u, int wr, int wc, int fr, int fq) const {
;     ...
;         for (int ai = 0; ai < 2; ++ai) { float rsv[4]; row_rstd4(ssq, row0 + ai * 128, fq, rsv);
; #pragma unroll
;             for (int m = 0; m < 4; ++m) {
;                 const int row = row0 + ai * 128 + m * 16; const float rs = rsv[m], c = -rs * LOG2E, rs2 = rs * rs;
;                 f32x4 e0 = acc[ai][0][m][0] * c, e1 = acc[ai][0][m][1] * c;
.LBB0_1224:
	s_cmp_lg_u32 s32, 0
	s_cbranch_scc1 .Lrc_a1
	v_lshl_add_u32 v254, s20, 8, v148
	v_mov_b32_e32 v172, v254
	v_ashrrev_i32_e32 v173, 31, v172
	v_lshlrev_b64 v[172:173], 6, v[172:173]
	v_lshl_add_u64 v[172:173], v[134:135], 0, v[172:173]
	global_load_dwordx4 v[172:175], v[172:173], off
	v_add_u32_e32 v176, 16, v254
	v_ashrrev_i32_e32 v177, 31, v176
	v_lshlrev_b64 v[176:177], 6, v[176:177]
	v_lshl_add_u64 v[176:177], v[134:135], 0, v[176:177]
	global_load_dwordx4 v[176:179], v[176:177], off
	v_add_u32_e32 v180, 32, v254
	v_ashrrev_i32_e32 v181, 31, v180
	v_lshlrev_b64 v[180:181], 6, v[180:181]
	v_lshl_add_u64 v[180:181], v[134:135], 0, v[180:181]
	global_load_dwordx4 v[180:183], v[180:181], off
	v_add_u32_e32 v184, 48, v254
	v_ashrrev_i32_e32 v185, 31, v184
	v_lshlrev_b64 v[184:185], 6, v[184:185]
	v_lshl_add_u64 v[184:185], v[134:135], 0, v[184:185]
	global_load_dwordx4 v[184:187], v[184:185], off
	v_add_u32_e32 v188, 0x80, v254
	v_ashrrev_i32_e32 v189, 31, v188
	v_lshlrev_b64 v[188:189], 6, v[188:189]
	v_lshl_add_u64 v[188:189], v[134:135], 0, v[188:189]
	global_load_dwordx4 v[188:191], v[188:189], off
	v_add_u32_e32 v218, 0x90, v254
	v_ashrrev_i32_e32 v219, 31, v218
	v_lshlrev_b64 v[218:219], 6, v[218:219]
	v_lshl_add_u64 v[218:219], v[134:135], 0, v[218:219]
	global_load_dwordx4 v[218:221], v[218:219], off
	v_add_u32_e32 v222, 0xa0, v254
	v_ashrrev_i32_e32 v223, 31, v222
	v_lshlrev_b64 v[222:223], 6, v[222:223]
	v_lshl_add_u64 v[222:223], v[134:135], 0, v[222:223]
	global_load_dwordx4 v[222:225], v[222:223], off
	v_add_u32_e32 v226, 0xb0, v254
	v_ashrrev_i32_e32 v227, 31, v226
	v_lshlrev_b64 v[226:227], 6, v[226:227]
	v_lshl_add_u64 v[226:227], v[134:135], 0, v[226:227]
	global_load_dwordx4 v[226:229], v[226:227], off
	v_xor_b32_e32 v202, 16, v215
	v_xor_b32_e32 v214, 32, v215
	v_lshlrev_b32_e32 v202, 2, v202
	v_lshlrev_b32_e32 v214, 2, v214
.Lrc_a1:
	v_lshl_add_u32 v140, s20, 8, v148
	v_or_b32_e32 v146, 16, v140
	v_or_b32_e32 v144, 32, v140
	v_or_b32_e32 v142, 48, v140
	v_ashrrev_i32_e32 v143, 31, v142
	v_lshlrev_b64 v[164:165], 6, v[142:143]
	v_lshl_add_u64 v[164:165], v[134:135], 0, v[164:165]
	v_and_b32_e32 v143, 64, v215
	v_xor_b32_e32 v141, 16, v215
	v_add_u32_e32 v143, 64, v143
	v_xor_b32_e32 v145, 32, v215
	v_cmp_lt_i32_e32 vcc, v141, v143
	v_pk_mul_f32 v[126:127], v[118:119], v[126:127]
	v_pk_mul_f32 v[124:125], v[116:117], v[124:125]
	v_cndmask_b32_e32 v141, v215, v141, vcc
	v_cmp_lt_i32_e32 vcc, v145, v143
	v_lshlrev_b32_e32 v141, 2, v141
	v_pk_mul_f32 v[120:121], v[112:113], v[120:121]
	v_cndmask_b32_e32 v143, v215, v145, vcc
	v_lshlrev_b32_e32 v143, 2, v143
	v_pk_mul_f32 v[122:123], v[114:115], v[122:123]
	v_lshl_or_b32 v168, s66, 7, v150
	v_ashrrev_i32_e32 v169, 31, v168
	v_pk_mul_f32 v[100:101], v[108:109], v[100:101]
	v_pk_mul_f32 v[102:103], v[110:111], v[102:103]
	v_pk_mul_f32 v[98:99], v[106:107], v[98:99]
	v_pk_mul_f32 v[96:97], v[104:105], v[96:97]
	v_pk_mul_f32 v[84:85], v[92:93], v[84:85]
	v_pk_mul_f32 v[86:87], v[94:95], v[86:87]
	v_pk_mul_f32 v[82:83], v[90:91], v[82:83]
	v_pk_mul_f32 v[80:81], v[88:89], v[80:81]
	v_pk_mul_f32 v[68:69], v[76:77], v[68:69]
	v_pk_mul_f32 v[70:71], v[78:79], v[70:71]
	v_pk_mul_f32 v[66:67], v[74:75], v[66:67]
	v_pk_mul_f32 v[64:65], v[72:73], v[64:65]
	v_pk_mul_f32 v[52:53], v[60:61], v[52:53]
	v_pk_mul_f32 v[54:55], v[62:63], v[54:55]
	v_pk_mul_f32 v[50:51], v[58:59], v[50:51]
	v_pk_mul_f32 v[48:49], v[56:57], v[48:49]
	v_pk_mul_f32 v[36:37], v[44:45], v[36:37]
	v_pk_mul_f32 v[38:39], v[46:47], v[38:39]
	v_pk_mul_f32 v[34:35], v[42:43], v[34:35]
	v_pk_mul_f32 v[32:33], v[40:41], v[32:33]
	v_pk_mul_f32 v[20:21], v[28:29], v[20:21]
	v_pk_mul_f32 v[22:23], v[30:31], v[22:23]
	v_pk_mul_f32 v[18:19], v[26:27], v[18:19]
	v_pk_mul_f32 v[16:17], v[24:25], v[16:17]
	v_pk_mul_f32 v[4:5], v[12:13], v[4:5]
	v_pk_mul_f32 v[6:7], v[14:15], v[6:7]
	v_pk_mul_f32 v[2:3], v[10:11], v[2:3]
	v_pk_mul_f32 v[0:1], v[8:9], v[0:1]
	s_andn2_b64 vcc, exec, s[4:5]
	s_mov_b64 s[4:5], -1
	s_cmp_lg_u32 s32, 0
	s_cbranch_scc1 .Lrc_b1
	s_waitcnt vmcnt(0)
	v_add_f32_e32 v172, v172, v173
	v_add_f32_e32 v174, v174, v175
	v_add_f32_e32 v176, v176, v177
	v_add_f32_e32 v178, v178, v179
	v_add_f32_e32 v180, v180, v181
	v_add_f32_e32 v182, v182, v183
	v_add_f32_e32 v184, v184, v185
	v_add_f32_e32 v186, v186, v187
	v_add_f32_e32 v188, v188, v189
	v_add_f32_e32 v190, v190, v191
	v_add_f32_e32 v218, v218, v219
	v_add_f32_e32 v220, v220, v221
	v_add_f32_e32 v222, v222, v223
	v_add_f32_e32 v224, v224, v225
	v_add_f32_e32 v226, v226, v227
	v_add_f32_e32 v228, v228, v229
	v_add_f32_e32 v172, v172, v174
	v_add_f32_e32 v176, v176, v178
	v_add_f32_e32 v180, v180, v182
	v_add_f32_e32 v184, v184, v186
	v_add_f32_e32 v188, v188, v190
	v_add_f32_e32 v218, v218, v220
	v_add_f32_e32 v222, v222, v224
	v_add_f32_e32 v226, v226, v228
	ds_bpermute_b32 v173, v202, v172
	ds_bpermute_b32 v177, v202, v176
	ds_bpermute_b32 v181, v202, v180
	ds_bpermute_b32 v185, v202, v184
	ds_bpermute_b32 v189, v202, v188
	ds_bpermute_b32 v219, v202, v218
	ds_bpermute_b32 v223, v202, v222
	ds_bpermute_b32 v227, v202, v226
	s_waitcnt lgkmcnt(0)
	v_add_f32_e32 v172, v172, v173
	v_add_f32_e32 v176, v176, v177
	v_add_f32_e32 v180, v180, v181
	v_add_f32_e32 v184, v184, v185
	v_add_f32_e32 v188, v188, v189
	v_add_f32_e32 v218, v218, v219
	v_add_f32_e32 v222, v222, v223
	v_add_f32_e32 v226, v226, v227
	ds_bpermute_b32 v173, v214, v172
	ds_bpermute_b32 v177, v214, v176
	ds_bpermute_b32 v181, v214, v180
	ds_bpermute_b32 v185, v214, v184
	ds_bpermute_b32 v189, v214, v188
	ds_bpermute_b32 v219, v214, v218
	ds_bpermute_b32 v223, v214, v222
	ds_bpermute_b32 v227, v214, v226
	s_waitcnt lgkmcnt(0)
	v_add_f32_e32 v172, v172, v173
	v_add_f32_e32 v176, v176, v177
	v_add_f32_e32 v180, v180, v181
	v_add_f32_e32 v184, v184, v185
	v_add_f32_e32 v188, v188, v189
	v_add_f32_e32 v218, v218, v219
	v_add_f32_e32 v222, v222, v223
	v_add_f32_e32 v226, v226, v227
	v_fmamk_f32 v172, v172, 0x3a800000, v212
	v_fmamk_f32 v176, v176, 0x3a800000, v212
	v_fmamk_f32 v180, v180, 0x3a800000, v212
	v_fmamk_f32 v184, v184, 0x3a800000, v212
	v_fmamk_f32 v188, v188, 0x3a800000, v212
	v_fmamk_f32 v218, v218, 0x3a800000, v212
	v_fmamk_f32 v222, v222, 0x3a800000, v212
	v_fmamk_f32 v226, v226, 0x3a800000, v212
	v_rsq_f32_e32 v236, v172
	v_rsq_f32_e32 v237, v176
	v_rsq_f32_e32 v238, v180
	v_rsq_f32_e32 v239, v184
	v_rsq_f32_e32 v240, v188
	v_rsq_f32_e32 v241, v218
	v_rsq_f32_e32 v252, v222
	v_rsq_f32_e32 v253, v226
	s_nop 0
	s_mov_b32 s32, 1
; __device__ __forceinline__ v4u pack8(const f32x4 a, const f32x4 b) { v4u w; w.x = cvt_pk_bf16(a[0], a[1]); w.y = cvt_pk_bf16(a[2], a[3]); w.z = cvt_pk_bf16(b[0], b[1]); w.w = cvt_pk_bf16(b[2], b[3]); return w; }
;     __device__ __forceinline__ void operator()(const f32x4 (&acc)[2][2][4][2], const pg8::Unit& u, int wr, int wc, int fr, int fq) const {
;     ...
;         for (int ai = 0; ai < 2; ++ai) { float rsv[4]; row_rstd4(ssq, row0 + ai * 128, fq, rsv);
; #pragma unroll
;             for (int m = 0; m < 4; ++m) {
;                 const int row = row0 + ai * 128 + m * 16; const float rs = rsv[m], c = -rs * LOG2E, rs2 = rs * rs;
;                 f32x4 e0 = acc[ai][0][m][0] * c, e1 = acc[ai][0][m][1] * c;
; #pragma unroll
;                 for (int i = 0; i < 4; ++i) { e0[i] = __builtin_amdgcn_exp2f(e0[i]); e1[i] = __builtin_amdgcn_exp2f(e1[i]); }
;                 e0 = e0 + 1.0f; e1 = e1 + 1.0f;
; #pragma unroll
;                 for (int i = 0; i < 4; ++i) { e0[i] = __builtin_amdgcn_rcpf(e0[i]); e1[i] = __builtin_amdgcn_rcpf(e1[i]); }
;                 const f32x4 h0 = (acc[ai][0][m][0] * acc[ai][1][m][0]) * rs2 * e0, h1 = (acc[ai][0][m][1] * acc[ai][1][m][1]) * rs2 * e1;
;                 *(v4u*)(O + (size_t)row * FFH + col0) = pack8(h0, h1);
.Lrc_b1:
	s_waitcnt lgkmcnt(0)
	s_waitcnt lgkmcnt(0)
	s_waitcnt lgkmcnt(0)
	s_waitcnt lgkmcnt(0)
	s_waitcnt lgkmcnt(0)
	s_waitcnt lgkmcnt(0)
	s_waitcnt lgkmcnt(0)
	s_waitcnt lgkmcnt(0)
	s_waitcnt lgkmcnt(0)
	v_mov_b32_e32 v145, v236
	v_mov_b32_e32 v153, v239
	v_mov_b32_e32 v155, v238
	v_mul_f32_e32 v152, 0xbfb8aa3b, v145
	v_pk_mul_f32 v[118:119], v[118:119], v[152:153] op_sel_hi:[1,0]
	v_pk_mul_f32 v[116:117], v[116:117], v[152:153] op_sel_hi:[1,0]
	v_pk_mul_f32 v[112:113], v[112:113], v[152:153] op_sel_hi:[1,0]
	v_pk_mul_f32 v[114:115], v[114:115], v[152:153] op_sel_hi:[1,0]
	v_exp_f32_e32 v116, v116
	v_exp_f32_e32 v112, v112
	v_exp_f32_e32 v117, v117
	v_exp_f32_e32 v118, v118
	v_exp_f32_e32 v119, v119
	v_exp_f32_e32 v113, v113
	v_exp_f32_e32 v114, v114
	v_exp_f32_e32 v115, v115
	v_pk_add_f32 v[118:119], v[118:119], 1.0 op_sel_hi:[1,0]
	v_pk_add_f32 v[116:117], v[116:117], 1.0 op_sel_hi:[1,0]
	v_pk_add_f32 v[112:113], v[112:113], 1.0 op_sel_hi:[1,0]
	v_pk_add_f32 v[114:115], v[114:115], 1.0 op_sel_hi:[1,0]
	v_rcp_f32_e32 v116, v116
	v_rcp_f32_e32 v112, v112
	v_rcp_f32_e32 v117, v117
	v_rcp_f32_e32 v118, v118
	v_rcp_f32_e32 v119, v119
	v_rcp_f32_e32 v113, v113
	v_rcp_f32_e32 v114, v114
	v_rcp_f32_e32 v115, v115
	v_mul_f32_e32 v154, v145, v145
	v_pk_mul_f32 v[124:125], v[124:125], v[154:155] op_sel_hi:[1,0]
	v_pk_mul_f32 v[126:127], v[126:127], v[154:155] op_sel_hi:[1,0]
	v_pk_mul_f32 v[120:121], v[120:121], v[154:155] op_sel_hi:[1,0]
	v_mov_b32_e32 v147, v237
	v_pk_mul_f32 v[122:123], v[122:123], v[154:155] op_sel_hi:[1,0]
	v_pk_mul_f32 v[118:119], v[126:127], v[118:119]
	v_pk_mul_f32 v[116:117], v[124:125], v[116:117]
	v_pk_mul_f32 v[112:113], v[120:121], v[112:113]
	v_pk_mul_f32 v[114:115], v[122:123], v[114:115]
	v_cvt_pk_bf16_f32 v116, v116, v117
	v_cvt_pk_bf16_f32 v117, v118, v119
	v_cvt_pk_bf16_f32 v118, v112, v113
	v_mov_b64_e32 v[112:113], s[8:9]
	v_cvt_pk_bf16_f32 v119, v114, v115
	v_mad_i64_i32 v[120:121], s[22:23], v140, s3, v[112:113]
	v_lshlrev_b64 v[114:115], 1, v[168:169]
	v_lshl_add_u64 v[120:121], v[120:121], 0, v[114:115]
	global_store_dwordx4 v[120:121], v[116:119], off
	v_mul_f32_e32 v124, v147, v147
	v_pk_mul_f32 v[100:101], v[100:101], v[124:125] op_sel_hi:[1,0]
	v_mul_f32_e32 v116, 0xbfb8aa3b, v147
	v_pk_mul_f32 v[120:121], v[108:109], v[116:117] op_sel_hi:[1,0]
	v_pk_mul_f32 v[118:119], v[110:111], v[116:117] op_sel_hi:[1,0]
	v_pk_mul_f32 v[122:123], v[106:107], v[116:117] op_sel_hi:[1,0]
	v_pk_mul_f32 v[116:117], v[104:105], v[116:117] op_sel_hi:[1,0]
	v_exp_f32_e32 v120, v120
	v_exp_f32_e32 v121, v121
	v_exp_f32_e32 v116, v116
	v_exp_f32_e32 v118, v118
	v_exp_f32_e32 v119, v119
	v_exp_f32_e32 v122, v122
	v_exp_f32_e32 v123, v123
	v_exp_f32_e32 v117, v117
	v_pk_add_f32 v[120:121], v[120:121], 1.0 op_sel_hi:[1,0]
	v_pk_add_f32 v[118:119], v[118:119], 1.0 op_sel_hi:[1,0]
	v_pk_add_f32 v[122:123], v[122:123], 1.0 op_sel_hi:[1,0]
	v_pk_add_f32 v[116:117], v[116:117], 1.0 op_sel_hi:[1,0]
	v_rcp_f32_e32 v120, v120
	v_rcp_f32_e32 v121, v121
	v_rcp_f32_e32 v116, v116
	v_rcp_f32_e32 v117, v117
	v_rcp_f32_e32 v118, v118
	v_rcp_f32_e32 v122, v122
	v_rcp_f32_e32 v119, v119
	v_rcp_f32_e32 v123, v123
	v_pk_mul_f32 v[102:103], v[102:103], v[124:125] op_sel_hi:[1,0]
	v_pk_mul_f32 v[100:101], v[100:101], v[120:121]
	v_pk_mul_f32 v[96:97], v[96:97], v[124:125] op_sel_hi:[1,0]
	v_pk_mul_f32 v[98:99], v[98:99], v[124:125] op_sel_hi:[1,0]
	v_pk_mul_f32 v[102:103], v[102:103], v[118:119]
	v_pk_mul_f32 v[104:105], v[98:99], v[122:123]
	v_pk_mul_f32 v[98:99], v[96:97], v[116:117]
	v_cvt_pk_bf16_f32 v96, v100, v101
	v_mad_i64_i32 v[100:101], s[22:23], v146, s3, v[112:113]
	v_cvt_pk_bf16_f32 v97, v102, v103
	v_cvt_pk_bf16_f32 v98, v98, v99
	v_cvt_pk_bf16_f32 v99, v104, v105
	v_lshl_add_u64 v[100:101], v[100:101], 0, v[114:115]
	global_store_dwordx4 v[100:101], v[96:99], off
	v_mul_f32_e32 v104, v155, v155
	v_pk_mul_f32 v[84:85], v[84:85], v[104:105] op_sel_hi:[1,0]
	v_mul_f32_e32 v96, 0xbfb8aa3b, v155
	v_pk_mul_f32 v[100:101], v[92:93], v[96:97] op_sel_hi:[1,0]
	v_pk_mul_f32 v[98:99], v[94:95], v[96:97] op_sel_hi:[1,0]
	v_pk_mul_f32 v[102:103], v[90:91], v[96:97] op_sel_hi:[1,0]
	v_pk_mul_f32 v[96:97], v[88:89], v[96:97] op_sel_hi:[1,0]
	v_exp_f32_e32 v100, v100
	v_exp_f32_e32 v101, v101
	v_exp_f32_e32 v96, v96
	v_exp_f32_e32 v98, v98
	v_exp_f32_e32 v99, v99
	v_exp_f32_e32 v102, v102
	v_exp_f32_e32 v103, v103
	v_exp_f32_e32 v97, v97
	v_pk_add_f32 v[100:101], v[100:101], 1.0 op_sel_hi:[1,0]
	v_pk_add_f32 v[98:99], v[98:99], 1.0 op_sel_hi:[1,0]
	v_pk_add_f32 v[102:103], v[102:103], 1.0 op_sel_hi:[1,0]
	v_pk_add_f32 v[96:97], v[96:97], 1.0 op_sel_hi:[1,0]
	v_rcp_f32_e32 v100, v100
	v_rcp_f32_e32 v101, v101
	v_rcp_f32_e32 v96, v96
	v_rcp_f32_e32 v97, v97
	v_rcp_f32_e32 v98, v98
	v_rcp_f32_e32 v102, v102
	v_rcp_f32_e32 v99, v99
	v_rcp_f32_e32 v103, v103
	v_pk_mul_f32 v[86:87], v[86:87], v[104:105] op_sel_hi:[1,0]
	v_pk_mul_f32 v[84:85], v[84:85], v[100:101]
	v_pk_mul_f32 v[80:81], v[80:81], v[104:105] op_sel_hi:[1,0]
	v_pk_mul_f32 v[82:83], v[82:83], v[104:105] op_sel_hi:[1,0]
	v_pk_mul_f32 v[86:87], v[86:87], v[98:99]
	v_pk_mul_f32 v[88:89], v[82:83], v[102:103]
	v_pk_mul_f32 v[82:83], v[80:81], v[96:97]
	v_cvt_pk_bf16_f32 v80, v84, v85
	v_mad_i64_i32 v[84:85], s[22:23], v144, s3, v[112:113]
	v_cvt_pk_bf16_f32 v81, v86, v87
	v_cvt_pk_bf16_f32 v82, v82, v83
	v_cvt_pk_bf16_f32 v83, v88, v89
	v_lshl_add_u64 v[84:85], v[84:85], 0, v[114:115]
	global_store_dwordx4 v[84:85], v[80:83], off
	v_mul_f32_e32 v88, v153, v153
	v_pk_mul_f32 v[68:69], v[68:69], v[88:89] op_sel_hi:[1,0]
	v_mul_f32_e32 v80, 0xbfb8aa3b, v153
	v_pk_mul_f32 v[84:85], v[76:77], v[80:81] op_sel_hi:[1,0]
; __device__ __forceinline__ v4u pack8(const f32x4 a, const f32x4 b) { v4u w; w.x = cvt_pk_bf16(a[0], a[1]); w.y = cvt_pk_bf16(a[2], a[3]); w.z = cvt_pk_bf16(b[0], b[1]); w.w = cvt_pk_bf16(b[2], b[3]); return w; }
; __device__ __forceinline__ void row_rstd4(const float* ssq, int row0, int fq, float (&rs)[4]) {
;     f32x4 v[4];
; #pragma unroll
;     for (int m = 0; m < 4; ++m) v[m] = *(const f32x4*)(ssq + (size_t)(row0 + m * 16) * 16 + fq * 4);
; #pragma unroll
;     for (int m = 0; m < 4; ++m) { float t = (v[m][0] + v[m][1]) + (v[m][2] + v[m][3]); t += __shfl_xor(t, 16); t += __shfl_xor(t, 32); rs[m] = __builtin_amdgcn_rsqf(t * (1.f / DM) + EPS); }
; }
;     __device__ __forceinline__ void operator()(const f32x4 (&acc)[2][2][4][2], const pg8::Unit& u, int wr, int wc, int fr, int fq) const {
;     ...
;                 const int row = row0 + ai * 128 + m * 16; const float rs = rsv[m], c = -rs * LOG2E, rs2 = rs * rs;
;                 f32x4 e0 = acc[ai][0][m][0] * c, e1 = acc[ai][0][m][1] * c;
; #pragma unroll
;                 for (int i = 0; i < 4; ++i) { e0[i] = __builtin_amdgcn_exp2f(e0[i]); e1[i] = __builtin_amdgcn_exp2f(e1[i]); }
;                 e0 = e0 + 1.0f; e1 = e1 + 1.0f;
; #pragma unroll
;                 for (int i = 0; i < 4; ++i) { e0[i] = __builtin_amdgcn_rcpf(e0[i]); e1[i] = __builtin_amdgcn_rcpf(e1[i]); }
;                 const f32x4 h0 = (acc[ai][0][m][0] * acc[ai][1][m][0]) * rs2 * e0, h1 = (acc[ai][0][m][1] * acc[ai][1][m][1]) * rs2 * e1;
;                 *(v4u*)(O + (size_t)row * FFH + col0) = pack8(h0, h1);
	v_pk_mul_f32 v[82:83], v[78:79], v[80:81] op_sel_hi:[1,0]
	v_pk_mul_f32 v[86:87], v[74:75], v[80:81] op_sel_hi:[1,0]
	v_pk_mul_f32 v[80:81], v[72:73], v[80:81] op_sel_hi:[1,0]
	v_exp_f32_e32 v84, v84
	v_exp_f32_e32 v85, v85
	v_exp_f32_e32 v80, v80
	v_exp_f32_e32 v82, v82
	v_exp_f32_e32 v83, v83
	v_exp_f32_e32 v86, v86
	v_exp_f32_e32 v87, v87
	v_exp_f32_e32 v81, v81
	v_pk_add_f32 v[84:85], v[84:85], 1.0 op_sel_hi:[1,0]
	v_pk_add_f32 v[82:83], v[82:83], 1.0 op_sel_hi:[1,0]
	v_pk_add_f32 v[86:87], v[86:87], 1.0 op_sel_hi:[1,0]
	v_pk_add_f32 v[80:81], v[80:81], 1.0 op_sel_hi:[1,0]
	v_rcp_f32_e32 v84, v84
	v_rcp_f32_e32 v85, v85
	v_rcp_f32_e32 v80, v80
	v_rcp_f32_e32 v81, v81
	v_rcp_f32_e32 v82, v82
	v_rcp_f32_e32 v86, v86
	v_rcp_f32_e32 v83, v83
	v_rcp_f32_e32 v87, v87
	v_pk_mul_f32 v[70:71], v[70:71], v[88:89] op_sel_hi:[1,0]
	v_pk_mul_f32 v[68:69], v[68:69], v[84:85]
	v_pk_mul_f32 v[64:65], v[64:65], v[88:89] op_sel_hi:[1,0]
	v_pk_mul_f32 v[66:67], v[66:67], v[88:89] op_sel_hi:[1,0]
	v_pk_mul_f32 v[70:71], v[70:71], v[82:83]
	v_pk_mul_f32 v[72:73], v[66:67], v[86:87]
	v_pk_mul_f32 v[66:67], v[64:65], v[80:81]
	v_cvt_pk_bf16_f32 v64, v68, v69
	v_mad_i64_i32 v[68:69], s[22:23], v142, s3, v[112:113]
	v_add_u32_e32 v84, 0x80, v140
	v_cvt_pk_bf16_f32 v65, v70, v71
	v_cvt_pk_bf16_f32 v66, v66, v67
	v_cvt_pk_bf16_f32 v67, v72, v73
	v_lshl_add_u64 v[68:69], v[68:69], 0, v[114:115]
	v_ashrrev_i32_e32 v85, 31, v84
	global_store_dwordx4 v[68:69], v[64:67], off
	v_add_u32_e32 v86, 0x90, v140
	v_ashrrev_i32_e32 v87, 31, v86
	v_add_u32_e32 v66, 0xa0, v140
	v_add_u32_e32 v64, 0xb0, v140
	v_ashrrev_i32_e32 v65, 31, v64
	v_lshlrev_b64 v[80:81], 6, v[64:65]
	v_lshl_add_u64 v[80:81], v[134:135], 0, v[80:81]
	s_waitcnt lgkmcnt(0)
	s_nop 0
	s_waitcnt lgkmcnt(0)
	s_waitcnt lgkmcnt(0)
	s_waitcnt lgkmcnt(0)
	s_waitcnt lgkmcnt(0)
	s_waitcnt lgkmcnt(0)
	s_waitcnt lgkmcnt(0)
	v_mov_b32_e32 v65, v240
	s_waitcnt lgkmcnt(0)
	s_waitcnt lgkmcnt(0)
; __device__ __forceinline__ v4u pack8(const f32x4 a, const f32x4 b) { v4u w; w.x = cvt_pk_bf16(a[0], a[1]); w.y = cvt_pk_bf16(a[2], a[3]); w.z = cvt_pk_bf16(b[0], b[1]); w.w = cvt_pk_bf16(b[2], b[3]); return w; }
;     __device__ __forceinline__ void operator()(const f32x4 (&acc)[2][2][4][2], const pg8::Unit& u, int wr, int wc, int fr, int fq) const {
;     ...
;                 const int row = row0 + ai * 128 + m * 16; const float rs = rsv[m], c = -rs * LOG2E, rs2 = rs * rs;
;                 f32x4 e0 = acc[ai][0][m][0] * c, e1 = acc[ai][0][m][1] * c;
; #pragma unroll
;                 for (int i = 0; i < 4; ++i) { e0[i] = __builtin_amdgcn_exp2f(e0[i]); e1[i] = __builtin_amdgcn_exp2f(e1[i]); }
;                 e0 = e0 + 1.0f; e1 = e1 + 1.0f;
; #pragma unroll
;                 for (int i = 0; i < 4; ++i) { e0[i] = __builtin_amdgcn_rcpf(e0[i]); e1[i] = __builtin_amdgcn_rcpf(e1[i]); }
;                 const f32x4 h0 = (acc[ai][0][m][0] * acc[ai][1][m][0]) * rs2 * e0, h1 = (acc[ai][0][m][1] * acc[ai][1][m][1]) * rs2 * e1;
;                 *(v4u*)(O + (size_t)row * FFH + col0) = pack8(h0, h1);
	v_mov_b32_e32 v78, v253
	v_mul_f32_e32 v68, 0xbfb8aa3b, v65
	v_pk_mul_f32 v[72:73], v[60:61], v[68:69] op_sel_hi:[1,0]
	v_mov_b32_e32 v77, v252
	v_pk_mul_f32 v[70:71], v[62:63], v[68:69] op_sel_hi:[1,0]
	v_pk_mul_f32 v[74:75], v[58:59], v[68:69] op_sel_hi:[1,0]
	v_pk_mul_f32 v[68:69], v[56:57], v[68:69] op_sel_hi:[1,0]
	v_exp_f32_e32 v72, v72
	v_exp_f32_e32 v73, v73
	v_exp_f32_e32 v68, v68
	v_exp_f32_e32 v70, v70
	v_exp_f32_e32 v71, v71
	v_exp_f32_e32 v74, v74
	v_exp_f32_e32 v75, v75
	v_exp_f32_e32 v69, v69
	v_pk_add_f32 v[72:73], v[72:73], 1.0 op_sel_hi:[1,0]
	v_pk_add_f32 v[70:71], v[70:71], 1.0 op_sel_hi:[1,0]
	v_pk_add_f32 v[74:75], v[74:75], 1.0 op_sel_hi:[1,0]
	v_pk_add_f32 v[68:69], v[68:69], 1.0 op_sel_hi:[1,0]
	v_rcp_f32_e32 v72, v72
	v_rcp_f32_e32 v73, v73
	v_rcp_f32_e32 v68, v68
	v_rcp_f32_e32 v69, v69
	v_rcp_f32_e32 v70, v70
	v_rcp_f32_e32 v74, v74
	v_rcp_f32_e32 v71, v71
	v_rcp_f32_e32 v75, v75
	v_mul_f32_e32 v76, v65, v65
	v_mov_b32_e32 v67, v241
	v_pk_mul_f32 v[52:53], v[52:53], v[76:77] op_sel_hi:[1,0]
	v_pk_mul_f32 v[54:55], v[54:55], v[76:77] op_sel_hi:[1,0]
	v_pk_mul_f32 v[52:53], v[52:53], v[72:73]
	v_pk_mul_f32 v[48:49], v[48:49], v[76:77] op_sel_hi:[1,0]
	v_pk_mul_f32 v[50:51], v[50:51], v[76:77] op_sel_hi:[1,0]
	v_pk_mul_f32 v[54:55], v[54:55], v[70:71]
	v_pk_mul_f32 v[56:57], v[50:51], v[74:75]
	v_pk_mul_f32 v[50:51], v[48:49], v[68:69]
	v_cvt_pk_bf16_f32 v48, v52, v53
	v_mad_i64_i32 v[52:53], s[22:23], v84, s3, v[112:113]
	v_cvt_pk_bf16_f32 v49, v54, v55
	v_cvt_pk_bf16_f32 v50, v50, v51
	v_cvt_pk_bf16_f32 v51, v56, v57
	v_lshl_add_u64 v[52:53], v[52:53], 0, v[114:115]
	global_store_dwordx4 v[52:53], v[48:51], off
	v_mul_f32_e32 v56, v67, v67
	v_pk_mul_f32 v[36:37], v[36:37], v[56:57] op_sel_hi:[1,0]
	v_mul_f32_e32 v48, 0xbfb8aa3b, v67
	v_pk_mul_f32 v[52:53], v[44:45], v[48:49] op_sel_hi:[1,0]
	v_pk_mul_f32 v[50:51], v[46:47], v[48:49] op_sel_hi:[1,0]
	v_pk_mul_f32 v[54:55], v[42:43], v[48:49] op_sel_hi:[1,0]
	v_pk_mul_f32 v[48:49], v[40:41], v[48:49] op_sel_hi:[1,0]
	v_exp_f32_e32 v52, v52
	v_exp_f32_e32 v53, v53
	v_exp_f32_e32 v48, v48
	v_exp_f32_e32 v50, v50
	v_exp_f32_e32 v51, v51
	v_exp_f32_e32 v54, v54
	v_exp_f32_e32 v55, v55
	v_exp_f32_e32 v49, v49
	v_pk_add_f32 v[52:53], v[52:53], 1.0 op_sel_hi:[1,0]
	v_pk_add_f32 v[50:51], v[50:51], 1.0 op_sel_hi:[1,0]
	v_pk_add_f32 v[54:55], v[54:55], 1.0 op_sel_hi:[1,0]
	v_pk_add_f32 v[48:49], v[48:49], 1.0 op_sel_hi:[1,0]
	v_rcp_f32_e32 v52, v52
	v_rcp_f32_e32 v53, v53
	v_rcp_f32_e32 v48, v48
	v_rcp_f32_e32 v49, v49
	v_rcp_f32_e32 v50, v50
	v_rcp_f32_e32 v54, v54
	v_rcp_f32_e32 v51, v51
	v_rcp_f32_e32 v55, v55
	v_pk_mul_f32 v[38:39], v[38:39], v[56:57] op_sel_hi:[1,0]
	v_pk_mul_f32 v[36:37], v[36:37], v[52:53]
	v_pk_mul_f32 v[32:33], v[32:33], v[56:57] op_sel_hi:[1,0]
	v_pk_mul_f32 v[34:35], v[34:35], v[56:57] op_sel_hi:[1,0]
	v_pk_mul_f32 v[38:39], v[38:39], v[50:51]
	v_pk_mul_f32 v[40:41], v[34:35], v[54:55]
	v_pk_mul_f32 v[34:35], v[32:33], v[48:49]
	v_cvt_pk_bf16_f32 v32, v36, v37
	v_mad_i64_i32 v[36:37], s[22:23], v86, s3, v[112:113]
	v_cvt_pk_bf16_f32 v33, v38, v39
	v_cvt_pk_bf16_f32 v34, v34, v35
	v_cvt_pk_bf16_f32 v35, v40, v41
	v_lshl_add_u64 v[36:37], v[36:37], 0, v[114:115]
	global_store_dwordx4 v[36:37], v[32:35], off
	v_mul_f32_e32 v40, v77, v77
	v_pk_mul_f32 v[20:21], v[20:21], v[40:41] op_sel_hi:[1,0]
	v_mul_f32_e32 v32, 0xbfb8aa3b, v77
	v_pk_mul_f32 v[36:37], v[28:29], v[32:33] op_sel_hi:[1,0]
	v_pk_mul_f32 v[34:35], v[30:31], v[32:33] op_sel_hi:[1,0]
	v_pk_mul_f32 v[38:39], v[26:27], v[32:33] op_sel_hi:[1,0]
	v_pk_mul_f32 v[32:33], v[24:25], v[32:33] op_sel_hi:[1,0]
	v_exp_f32_e32 v36, v36
	v_exp_f32_e32 v37, v37
	v_exp_f32_e32 v32, v32
	v_exp_f32_e32 v34, v34
	v_exp_f32_e32 v35, v35
	v_exp_f32_e32 v38, v38
	v_exp_f32_e32 v39, v39
	v_exp_f32_e32 v33, v33
	v_pk_add_f32 v[36:37], v[36:37], 1.0 op_sel_hi:[1,0]
	v_pk_add_f32 v[34:35], v[34:35], 1.0 op_sel_hi:[1,0]
	v_pk_add_f32 v[38:39], v[38:39], 1.0 op_sel_hi:[1,0]
	v_pk_add_f32 v[32:33], v[32:33], 1.0 op_sel_hi:[1,0]
	v_rcp_f32_e32 v36, v36
	v_rcp_f32_e32 v37, v37
	v_rcp_f32_e32 v32, v32
	v_rcp_f32_e32 v33, v33
	v_rcp_f32_e32 v34, v34
	v_rcp_f32_e32 v38, v38
	v_rcp_f32_e32 v35, v35
	v_rcp_f32_e32 v39, v39
	v_pk_mul_f32 v[22:23], v[22:23], v[40:41] op_sel_hi:[1,0]
	v_pk_mul_f32 v[20:21], v[20:21], v[36:37]
	v_pk_mul_f32 v[16:17], v[16:17], v[40:41] op_sel_hi:[1,0]
	v_pk_mul_f32 v[18:19], v[18:19], v[40:41] op_sel_hi:[1,0]
	v_pk_mul_f32 v[22:23], v[22:23], v[34:35]
	v_pk_mul_f32 v[24:25], v[18:19], v[38:39]
	v_pk_mul_f32 v[18:19], v[16:17], v[32:33]
	v_cvt_pk_bf16_f32 v16, v20, v21
	v_mad_i64_i32 v[20:21], s[22:23], v66, s3, v[112:113]
	v_cvt_pk_bf16_f32 v17, v22, v23
	v_cvt_pk_bf16_f32 v18, v18, v19
	v_cvt_pk_bf16_f32 v19, v24, v25
	v_lshl_add_u64 v[20:21], v[20:21], 0, v[114:115]
	global_store_dwordx4 v[20:21], v[16:19], off
	v_mul_f32_e32 v24, v78, v78
	v_pk_mul_f32 v[4:5], v[4:5], v[24:25] op_sel_hi:[1,0]
	v_mul_f32_e32 v16, 0xbfb8aa3b, v78
	v_pk_mul_f32 v[20:21], v[12:13], v[16:17] op_sel_hi:[1,0]
	v_pk_mul_f32 v[18:19], v[14:15], v[16:17] op_sel_hi:[1,0]
	v_pk_mul_f32 v[22:23], v[10:11], v[16:17] op_sel_hi:[1,0]
	v_pk_mul_f32 v[16:17], v[8:9], v[16:17] op_sel_hi:[1,0]
	v_exp_f32_e32 v20, v20
	v_exp_f32_e32 v21, v21
	v_exp_f32_e32 v16, v16
	v_exp_f32_e32 v18, v18
	v_exp_f32_e32 v19, v19
	v_exp_f32_e32 v22, v22
	v_exp_f32_e32 v23, v23
	v_exp_f32_e32 v17, v17
	v_pk_add_f32 v[20:21], v[20:21], 1.0 op_sel_hi:[1,0]
	v_pk_add_f32 v[18:19], v[18:19], 1.0 op_sel_hi:[1,0]
	v_pk_add_f32 v[22:23], v[22:23], 1.0 op_sel_hi:[1,0]
	v_pk_add_f32 v[16:17], v[16:17], 1.0 op_sel_hi:[1,0]
	v_rcp_f32_e32 v20, v20
	v_rcp_f32_e32 v21, v21
	v_rcp_f32_e32 v16, v16
	v_rcp_f32_e32 v17, v17
	v_rcp_f32_e32 v18, v18
	v_rcp_f32_e32 v22, v22
	v_rcp_f32_e32 v19, v19
	v_rcp_f32_e32 v23, v23
	v_pk_mul_f32 v[6:7], v[6:7], v[24:25] op_sel_hi:[1,0]
	v_pk_mul_f32 v[4:5], v[4:5], v[20:21]
	v_pk_mul_f32 v[0:1], v[0:1], v[24:25] op_sel_hi:[1,0]
	v_pk_mul_f32 v[2:3], v[2:3], v[24:25] op_sel_hi:[1,0]
	v_pk_mul_f32 v[6:7], v[6:7], v[18:19]
	v_pk_mul_f32 v[8:9], v[2:3], v[22:23]
	v_pk_mul_f32 v[2:3], v[0:1], v[16:17]
	v_cvt_pk_bf16_f32 v0, v4, v5
	v_mad_i64_i32 v[4:5], s[22:23], v64, s3, v[112:113]
	v_cvt_pk_bf16_f32 v1, v6, v7
	v_cvt_pk_bf16_f32 v2, v2, v3
	v_cvt_pk_bf16_f32 v3, v8, v9
	v_lshl_add_u64 v[4:5], v[4:5], 0, v[114:115]
	global_store_dwordx4 v[4:5], v[0:3], off
	s_cbranch_vccnz .LBB0_1217
	s_andn2_b64 vcc, exec, s[6:7]
	s_cbranch_vccnz .LBB0_1216
	s_barrier
	s_branch .LBB0_1216
